# PH1 tail table loops re-mapped across workgroups 64..255 (KTAB / W2 / W3 no longer stacked on the same threads); PH0 single-row norm reuses preloaded g_mix
# speedup vs baseline: 1.0122x; 1.0068x over previous
; __device__ __forceinline__ unsigned cvt_pk_bf16(float lo, float hi) { unsigned r; asm volatile("v_cvt_pk_bf16_f32 %0, %1, %2" : "=v"(r) : "v"(lo), "v"(hi)); return r; }
; __global__ void __launch_bounds__(512, 2) fwd_kernel(Args a) {
;     ...
;                 const float ms = wave_sum(sq) * (1.0f / D) + EPS; const float rs = rsqrtf(ms);
;                 if (lane == 0) RINV[m] = sqrtf(ms);
; #pragma unroll
;                 for (int j = 0; j < 4; ++j) { const f32x4 gq = ((const f32x4*)g_mix)[lane + 64 * j]; const f32x4 y = v[j] * rs * gq;
;                     v2u w; w.x = cvt_pk_bf16(y[0], y[1]); w.y = cvt_pk_bf16(y[2], y[3]); o8[64 * j] = w; }
.LBB0_43:
	s_or_b64 exec, exec, s[24:25]
	v_mul_f32_e32 v40, 0x4b800000, v35
	v_cmp_gt_f32_e32 vcc, s34, v35
	s_nop 1
	v_cndmask_b32_e32 v35, v35, v40, vcc
	v_rsq_f32_e32 v35, v35
	s_nop 0
	v_mul_f32_e32 v40, 0x45800000, v35
	v_cndmask_b32_e32 v40, v35, v40, vcc
	v_pk_mul_f32 v[12:13], v[12:13], v[40:41] op_sel_hi:[1,0]
	v_pk_mul_f32 v[14:15], v[14:15], v[40:41] op_sel_hi:[1,0]
	v_pk_mul_f32 v[8:9], v[8:9], v[40:41] op_sel_hi:[1,0]
	v_pk_mul_f32 v[10:11], v[10:11], v[40:41] op_sel_hi:[1,0]
	v_pk_mul_f32 v[4:5], v[4:5], v[40:41] op_sel_hi:[1,0]
	v_pk_mul_f32 v[6:7], v[6:7], v[40:41] op_sel_hi:[1,0]
	v_pk_mul_f32 v[0:1], v[0:1], v[40:41] op_sel_hi:[1,0]
	v_pk_mul_f32 v[2:3], v[2:3], v[40:41] op_sel_hi:[1,0]
	v_pk_mul_f32 v[12:13], v[12:13], v[238:239]
	v_pk_mul_f32 v[14:15], v[14:15], v[240:241]
	v_cvt_pk_bf16_f32 v12, v12, v13
	s_nop 0
	v_cvt_pk_bf16_f32 v13, v14, v15
	global_store_dwordx2 v[22:23], v[12:13], off
	v_add_co_u32_e32 v22, vcc, s31, v20
	v_pk_mul_f32 v[8:9], v[8:9], v[242:243]
	v_addc_co_u32_e32 v23, vcc, 0, v21, vcc
	v_pk_mul_f32 v[10:11], v[10:11], v[244:245]
	v_cvt_pk_bf16_f32 v8, v8, v9
	s_nop 0
	v_cvt_pk_bf16_f32 v9, v10, v11
	global_store_dwordx2 v[22:23], v[8:9], off offset:512
	v_pk_mul_f32 v[4:5], v[4:5], v[246:247]
	v_pk_mul_f32 v[6:7], v[6:7], v[248:249]
	v_cvt_pk_bf16_f32 v4, v4, v5
	s_nop 0
	v_cvt_pk_bf16_f32 v5, v6, v7
	global_store_dwordx2 v[22:23], v[4:5], off offset:1024
	v_pk_mul_f32 v[0:1], v[0:1], v[250:251]
	v_pk_mul_f32 v[2:3], v[2:3], v[252:253]
	v_cvt_pk_bf16_f32 v0, v0, v1
	s_nop 0
	v_cvt_pk_bf16_f32 v1, v2, v3

; __device__ __forceinline__ unsigned cvt_pk_bf16(float lo, float hi) { unsigned r; asm volatile("v_cvt_pk_bf16_f32 %0, %1, %2" : "=v"(r) : "v"(lo), "v"(hi)); return r; }
; __device__ __forceinline__ f32x2 cmul(f32x2 a, f32x2 b) { return (f32x2){a.x * b.x - a.y * b.y, a.x * b.y + a.y * b.x}; }
; __global__ void __launch_bounds__(512, 2) fwd_kernel(Args a) {
;     ...
;         for (size_t i = vt; i < (size_t)NG * NP * 16; i += VNT) {
;             const int j = (int)i & 15, p = ((int)i >> 4) & 63, g = (int)i >> 10; const int gp = g * NP + p;
;             const f32x2 cf = APW[gp * 17 + 15 - j];
;             unsigned wre[8], wim[8];
; #pragma unroll
;             for (int h = 0; h < NH; h += 2) {
;                 const f32x4 b2 = *(const f32x4*)(BBAR + (size_t)gp * NH + h);
;                 const f32x2 v0 = cmul(cf, (f32x2){b2[0], b2[1]}), v1 = cmul(cf, (f32x2){b2[2], b2[3]});
;                 wre[h >> 1] = cvt_pk_bf16(v0.x, v1.x); wim[h >> 1] = cvt_pk_bf16(v0.y, v1.y);
;             }
;             bf16* w2r = W2 + ((size_t)(g * 128 + 2 * p) * 256 + j * 16);
;             *(v4u*)(w2r) = (v4u){wre[0], wre[1], wre[2], wre[3]}; *(v4u*)(w2r + 8) = (v4u){wre[4], wre[5], wre[6], wre[7]};
;             *(v4u*)(w2r + 256) = (v4u){wim[0], wim[1], wim[2], wim[3]}; *(v4u*)(w2r + 264) = (v4u){wim[4], wim[5], wim[6], wim[7]};
;         }
.Lw2_entry:
	s_or_b64 exec, exec, s[22:23]
	v_add_co_u32_e32 v6, vcc, 0xffff8000, v0
	s_nop 1
	v_addc_co_u32_e32 v7, vcc, -1, v1, vcc
	s_mov_b64 s[0:1], 0x8000
	v_cmp_gt_u64_e32 vcc, s[0:1], v[6:7]
	s_and_saveexec_b64 s[22:23], vcc
	s_cbranch_execz .LBB0_215
	s_add_u32 s8, s20, 0x1540000
	s_addc_u32 s9, s21, 0
	s_add_u32 s24, s20, 0x1948000
	v_and_b32_e32 v3, 15, v152
	s_addc_u32 s25, s21, 0
	v_bitop3_b32 v2, v152, 15, v152 bitop3:0xc
	v_lshlrev_b32_e32 v3, 4, v3
	s_mov_b64 s[26:27], 0
	v_mov_b32_e32 v5, 0
	s_mov_b64 s[42:43], 0x7fff

; __device__ __forceinline__ unsigned cvt_pk_bf16(float lo, float hi) { unsigned r; asm volatile("v_cvt_pk_bf16_f32 %0, %1, %2" : "=v"(r) : "v"(lo), "v"(hi)); return r; }
; __device__ __forceinline__ f32x2 cmul(f32x2 a, f32x2 b) { return (f32x2){a.x * b.x - a.y * b.y, a.x * b.y + a.y * b.x}; }
; __global__ void __launch_bounds__(512, 2) fwd_kernel(Args a) {
;     ...
;         for (size_t i = vt; i < (size_t)NG * 16 * 16 * 16; i += VNT) {
;             const int pq = (int)i & 15, h = ((int)i >> 4) & 15, j = ((int)i >> 8) & 15, g = (int)i >> 12;
;             const f32x4 cr4 = *(const f32x4*)(c_re + (size_t)(g * NH + h) * NP + 4 * pq), ci4 = *(const f32x4*)(c_im + (size_t)(g * NH + h) * NP + 4 * pq);
;             unsigned w[4];
; #pragma unroll
;             for (int q = 0; q < 4; ++q) { const f32x2 v = cmul(APW[(g * NP + 4 * pq + q) * 17 + j + 1], (f32x2){cr4[q], ci4[q]}); w[q] = cvt_pk_bf16(v.x, -v.y); }
;             *(v4u*)(W3 + ((size_t)(g * 256 + j * 16 + h) * 128 + 8 * pq)) = (v4u){w[0], w[1], w[2], w[3]};
;         }
.LBB0_215:
	s_or_b64 exec, exec, s[22:23]
	v_add_co_u32_e32 v0, vcc, 0xffff8000, v0
	s_nop 1
	v_addc_co_u32_e32 v1, vcc, -1, v1, vcc
	s_mov_b64 s[18:19], 0x10000
	s_mov_b64 s[0:1], 0x20000
	v_cmp_gt_u64_e32 vcc, s[0:1], v[0:1]
	s_and_saveexec_b64 s[8:9], vcc
	s_cbranch_execz .LBB0_218
	v_and_b32_e32 v9, 15, v152
	v_lshlrev_b32_e32 v2, 4, v9
	v_mov_b32_e32 v3, 0
	s_add_u32 s20, s20, 0x1740000
	s_waitcnt lgkmcnt(0)
	v_lshl_add_u64 v[4:5], s[12:13], 0, v[2:3]
	v_lshl_add_u64 v[6:7], s[14:15], 0, v[2:3]
	v_lshlrev_b32_e32 v2, 3, v9
	s_addc_u32 s21, s21, 0
	v_lshlrev_b32_e32 v8, 2, v9
	s_mov_b64 s[12:13], 0
	v_lshlrev_b32_e32 v9, 1, v2
	s_mov_b64 s[14:15], 0x1ffff
